# layer-0 out-projection fused epilogue: the second-half f32 residual loads issued as one batch (3 groups up front, 4th after the first group is consumed) with counted vmcnt instead of four load-wait-us
# speedup vs baseline: 1.0005x; 1.0005x over previous
.LBB0_769:
	s_or_b64 exec, exec, s[4:5]
	v_readlane_b32 s4, v255, 8
	s_lshl_b32 s4, s4, 2
	s_add_i32 s4, s4, 0
	s_waitcnt vmcnt(0) lgkmcnt(0)
	s_barrier
	v_lshl_add_u32 v0, v247, 2, s4
	ds_read_b32 v230, v0 offset:8192
	v_pk_mul_f32 v[128:129], v[128:129], v[144:145]
	v_pk_mul_f32 v[126:127], v[126:127], v[142:143]
	v_pk_mul_f32 v[124:125], v[124:125], v[140:141]
	v_pk_mul_f32 v[122:123], v[122:123], v[138:139]
	v_pk_mul_f32 v[116:117], v[116:117], v[136:137]
	v_pk_mul_f32 v[114:115], v[114:115], v[134:135]
	v_pk_mul_f32 v[108:109], v[108:109], v[132:133]
	v_pk_mul_f32 v[106:107], v[106:107], v[130:131]
	s_waitcnt lgkmcnt(0)
	v_pk_fma_f32 v[128:129], v[128:129], v[230:231], v[208:209] op_sel_hi:[1,0,1]
	v_pk_fma_f32 v[126:127], v[126:127], v[230:231], v[206:207] op_sel_hi:[1,0,1]
	v_pk_fma_f32 v[124:125], v[124:125], v[230:231], v[204:205] op_sel_hi:[1,0,1]
	v_pk_fma_f32 v[122:123], v[122:123], v[230:231], v[202:203] op_sel_hi:[1,0,1]
	v_pk_fma_f32 v[116:117], v[116:117], v[230:231], v[200:201] op_sel_hi:[1,0,1]
	v_pk_fma_f32 v[114:115], v[114:115], v[230:231], v[198:199] op_sel_hi:[1,0,1]
	v_pk_fma_f32 v[108:109], v[108:109], v[230:231], v[196:197] op_sel_hi:[1,0,1]
	v_pk_fma_f32 v[106:107], v[106:107], v[230:231], v[194:195] op_sel_hi:[1,0,1]
	v_pk_mul_f32 v[120:121], v[120:121], v[144:145]
	ds_read_b32 v194, v0 offset:8256
	v_pk_mul_f32 v[118:119], v[118:119], v[142:143]
	v_pk_mul_f32 v[112:113], v[112:113], v[140:141]
	v_pk_mul_f32 v[110:111], v[110:111], v[138:139]
	v_pk_mul_f32 v[100:101], v[100:101], v[136:137]
	v_pk_mul_f32 v[98:99], v[98:99], v[134:135]
	v_pk_mul_f32 v[92:93], v[92:93], v[132:133]
	v_pk_mul_f32 v[90:91], v[90:91], v[130:131]
	s_waitcnt lgkmcnt(0)
	v_pk_fma_f32 v[120:121], v[120:121], v[194:195], v[192:193] op_sel_hi:[1,0,1]
	v_pk_fma_f32 v[118:119], v[118:119], v[194:195], v[190:191] op_sel_hi:[1,0,1]
	v_pk_fma_f32 v[112:113], v[112:113], v[194:195], v[188:189] op_sel_hi:[1,0,1]
	v_pk_fma_f32 v[110:111], v[110:111], v[194:195], v[186:187] op_sel_hi:[1,0,1]
	v_pk_fma_f32 v[100:101], v[100:101], v[194:195], v[184:185] op_sel_hi:[1,0,1]
	v_pk_fma_f32 v[98:99], v[98:99], v[194:195], v[182:183] op_sel_hi:[1,0,1]
	v_pk_fma_f32 v[92:93], v[92:93], v[194:195], v[180:181] op_sel_hi:[1,0,1]
	v_pk_fma_f32 v[90:91], v[90:91], v[194:195], v[178:179] op_sel_hi:[1,0,1]
	v_pk_mul_f32 v[104:105], v[104:105], v[144:145]
	ds_read_b32 v178, v0 offset:8320
	v_pk_mul_f32 v[102:103], v[102:103], v[142:143]
	v_pk_mul_f32 v[96:97], v[96:97], v[140:141]
	v_pk_mul_f32 v[94:95], v[94:95], v[138:139]
	v_pk_mul_f32 v[84:85], v[84:85], v[136:137]
	v_pk_mul_f32 v[82:83], v[82:83], v[134:135]
	v_pk_mul_f32 v[76:77], v[76:77], v[132:133]
	v_pk_mul_f32 v[74:75], v[74:75], v[130:131]
	s_waitcnt lgkmcnt(0)
	v_pk_fma_f32 v[104:105], v[104:105], v[178:179], v[176:177] op_sel_hi:[1,0,1]
	v_pk_fma_f32 v[102:103], v[102:103], v[178:179], v[174:175] op_sel_hi:[1,0,1]
	v_pk_fma_f32 v[96:97], v[96:97], v[178:179], v[172:173] op_sel_hi:[1,0,1]
	v_pk_fma_f32 v[94:95], v[94:95], v[178:179], v[170:171] op_sel_hi:[1,0,1]
	v_pk_fma_f32 v[84:85], v[84:85], v[178:179], v[168:169] op_sel_hi:[1,0,1]
	v_pk_fma_f32 v[82:83], v[82:83], v[178:179], v[166:167] op_sel_hi:[1,0,1]
	v_pk_fma_f32 v[76:77], v[76:77], v[178:179], v[164:165] op_sel_hi:[1,0,1]
	v_pk_fma_f32 v[74:75], v[74:75], v[178:179], v[162:163] op_sel_hi:[1,0,1]
	v_pk_mul_f32 v[88:89], v[88:89], v[144:145]
	ds_read_b32 v162, v0 offset:8384
	v_pk_mul_f32 v[86:87], v[86:87], v[142:143]
	v_pk_mul_f32 v[80:81], v[80:81], v[140:141]
	v_pk_mul_f32 v[78:79], v[78:79], v[138:139]
	v_pk_mul_f32 v[72:73], v[72:73], v[136:137]
	v_pk_mul_f32 v[70:71], v[70:71], v[134:135]
	v_pk_mul_f32 v[68:69], v[68:69], v[132:133]
	v_pk_mul_f32 v[66:67], v[66:67], v[130:131]
	s_mov_b32 s4, 0x80000
	s_waitcnt lgkmcnt(0)
	v_pk_fma_f32 v[88:89], v[88:89], v[162:163], v[160:161] op_sel_hi:[1,0,1]
	v_pk_fma_f32 v[86:87], v[86:87], v[162:163], v[158:159] op_sel_hi:[1,0,1]
	v_pk_fma_f32 v[80:81], v[80:81], v[162:163], v[156:157] op_sel_hi:[1,0,1]
	v_pk_fma_f32 v[78:79], v[78:79], v[162:163], v[154:155] op_sel_hi:[1,0,1]
	v_pk_fma_f32 v[72:73], v[72:73], v[162:163], v[152:153] op_sel_hi:[1,0,1]
	v_pk_fma_f32 v[70:71], v[70:71], v[162:163], v[150:151] op_sel_hi:[1,0,1]
	v_pk_fma_f32 v[68:69], v[68:69], v[162:163], v[148:149] op_sel_hi:[1,0,1]
	v_pk_fma_f32 v[66:67], v[66:67], v[162:163], v[146:147] op_sel_hi:[1,0,1]
	v_add_co_u32_e32 v158, vcc, s4, v220
	s_nop 1
	v_addc_co_u32_e32 v159, vcc, 0, v221, vcc
	global_load_dwordx4 v[146:149], v[158:159], off
	global_load_dwordx4 v[150:153], v[158:159], off offset:16
	global_load_dwordx4 v[154:157], v[158:159], off offset:512
	s_nop 0
	global_load_dwordx4 v[158:161], v[158:159], off offset:528
	v_add_co_u32_e32 v164, vcc, 0x90000, v220
	s_nop 1
	v_addc_co_u32_e32 v165, vcc, 0, v221, vcc
	global_load_dwordx4 v[166:169], v[164:165], off
	global_load_dwordx4 v[170:173], v[164:165], off offset:16
	global_load_dwordx4 v[174:177], v[164:165], off offset:512
	global_load_dwordx4 v[178:181], v[164:165], off offset:528
	v_add_co_u32_e32 v164, vcc, 0xa0000, v220
	s_nop 1
	v_addc_co_u32_e32 v165, vcc, 0, v221, vcc
	global_load_dwordx4 v[182:185], v[164:165], off
	global_load_dwordx4 v[186:189], v[164:165], off offset:16
	global_load_dwordx4 v[190:193], v[164:165], off offset:512
	global_load_dwordx4 v[194:197], v[164:165], off offset:528
	ds_read_b32 v162, v0 offset:8704
	v_pk_mul_f32 v[64:65], v[64:65], v[144:145]
	v_pk_mul_f32 v[62:63], v[62:63], v[142:143]
	v_pk_mul_f32 v[60:61], v[60:61], v[140:141]
	v_pk_mul_f32 v[58:59], v[58:59], v[138:139]
	v_pk_mul_f32 v[56:57], v[56:57], v[136:137]
	v_pk_mul_f32 v[54:55], v[54:55], v[134:135]
	v_pk_mul_f32 v[52:53], v[52:53], v[132:133]
	v_pk_mul_f32 v[50:51], v[50:51], v[130:131]
	v_pk_mul_f32 v[48:49], v[48:49], v[144:145]
	v_pk_mul_f32 v[46:47], v[46:47], v[142:143]
	v_pk_mul_f32 v[44:45], v[44:45], v[140:141]
	v_pk_mul_f32 v[42:43], v[42:43], v[138:139]
	v_pk_mul_f32 v[40:41], v[40:41], v[136:137]
	v_pk_mul_f32 v[38:39], v[38:39], v[134:135]
	v_pk_mul_f32 v[36:37], v[36:37], v[132:133]
	v_pk_mul_f32 v[34:35], v[34:35], v[130:131]
	v_pk_mul_f32 v[32:33], v[32:33], v[144:145]
	v_pk_mul_f32 v[30:31], v[30:31], v[142:143]
	v_pk_mul_f32 v[28:29], v[28:29], v[140:141]
	v_pk_mul_f32 v[26:27], v[26:27], v[138:139]
	v_pk_mul_f32 v[24:25], v[24:25], v[136:137]
	v_pk_mul_f32 v[22:23], v[22:23], v[134:135]
	v_pk_mul_f32 v[20:21], v[20:21], v[132:133]
	v_pk_mul_f32 v[18:19], v[18:19], v[130:131]
	v_pk_mul_f32 v[12:13], v[12:13], v[140:141]
	v_pk_mul_f32 v[2:3], v[2:3], v[130:131]
	v_pk_mul_f32 v[10:11], v[10:11], v[138:139]
	v_pk_mul_f32 v[4:5], v[4:5], v[132:133]
	v_pk_mul_f32 v[16:17], v[16:17], v[144:145]
	v_pk_mul_f32 v[14:15], v[14:15], v[142:143]
	v_pk_mul_f32 v[8:9], v[8:9], v[136:137]
	v_pk_mul_f32 v[6:7], v[6:7], v[134:135]
	s_waitcnt vmcnt(8) lgkmcnt(0)
	v_pk_fma_f32 v[64:65], v[64:65], v[162:163], v[148:149] op_sel_hi:[1,0,1]
	v_pk_fma_f32 v[62:63], v[62:63], v[162:163], v[146:147] op_sel_hi:[1,0,1]
	v_pk_fma_f32 v[60:61], v[60:61], v[162:163], v[152:153] op_sel_hi:[1,0,1]
	v_pk_fma_f32 v[58:59], v[58:59], v[162:163], v[150:151] op_sel_hi:[1,0,1]
	v_pk_fma_f32 v[56:57], v[56:57], v[162:163], v[156:157] op_sel_hi:[1,0,1]
	v_pk_fma_f32 v[54:55], v[54:55], v[162:163], v[154:155] op_sel_hi:[1,0,1]
	v_pk_fma_f32 v[52:53], v[52:53], v[162:163], v[160:161] op_sel_hi:[1,0,1]
	v_pk_fma_f32 v[50:51], v[50:51], v[162:163], v[158:159] op_sel_hi:[1,0,1]
	s_nop 0
	v_add_co_u32_e32 v164, vcc, 0xb0000, v220
	s_nop 1
	v_addc_co_u32_e32 v165, vcc, 0, v221, vcc
	global_load_dwordx4 v[146:149], v[164:165], off
	global_load_dwordx4 v[154:157], v[164:165], off offset:16
	global_load_dwordx4 v[158:161], v[164:165], off offset:512
	global_load_dwordx4 v[150:153], v[164:165], off offset:528
	ds_read_b32 v162, v0 offset:8768
	s_waitcnt vmcnt(8) lgkmcnt(0)
	v_pk_fma_f32 v[48:49], v[48:49], v[162:163], v[168:169] op_sel_hi:[1,0,1]
	v_pk_fma_f32 v[46:47], v[46:47], v[162:163], v[166:167] op_sel_hi:[1,0,1]
	v_pk_fma_f32 v[44:45], v[44:45], v[162:163], v[172:173] op_sel_hi:[1,0,1]
	v_pk_fma_f32 v[42:43], v[42:43], v[162:163], v[170:171] op_sel_hi:[1,0,1]
	v_pk_fma_f32 v[40:41], v[40:41], v[162:163], v[176:177] op_sel_hi:[1,0,1]
	v_pk_fma_f32 v[38:39], v[38:39], v[162:163], v[174:175] op_sel_hi:[1,0,1]
	v_pk_fma_f32 v[36:37], v[36:37], v[162:163], v[180:181] op_sel_hi:[1,0,1]
	v_pk_fma_f32 v[34:35], v[34:35], v[162:163], v[178:179] op_sel_hi:[1,0,1]
	s_nop 0
	ds_read_b32 v162, v0 offset:8832
	v_readlane_b32 s4, v254, 57
	v_readlane_b32 s5, v254, 58
	s_add_u32 s4, s4, s26
	s_addc_u32 s5, s5, s27
	v_lshl_add_u64 v[130:131], v[218:219], 2, s[4:5]
	s_mov_b64 s[4:5], 0x4000
	v_lshl_add_u64 v[138:139], v[130:131], 0, s[4:5]
	s_mov_b64 s[4:5], 0x3000
	v_lshl_add_u64 v[166:167], v[130:131], 0, s[4:5]
	s_movk_i32 s4, 0x4000
	v_add_co_u32_e32 v132, vcc, s4, v130
	s_movk_i32 s4, 0x3000
	s_nop 0
	v_addc_co_u32_e32 v133, vcc, 0, v131, vcc
	v_add_co_u32_e32 v130, vcc, s4, v130
	s_waitcnt vmcnt(4) lgkmcnt(0)
	v_pk_fma_f32 v[32:33], v[32:33], v[162:163], v[184:185] op_sel_hi:[1,0,1]
	v_pk_fma_f32 v[30:31], v[30:31], v[162:163], v[182:183] op_sel_hi:[1,0,1]
	v_pk_fma_f32 v[28:29], v[28:29], v[162:163], v[188:189] op_sel_hi:[1,0,1]
	v_pk_fma_f32 v[26:27], v[26:27], v[162:163], v[186:187] op_sel_hi:[1,0,1]
	v_pk_fma_f32 v[24:25], v[24:25], v[162:163], v[192:193] op_sel_hi:[1,0,1]
	v_pk_fma_f32 v[22:23], v[22:23], v[162:163], v[190:191] op_sel_hi:[1,0,1]
	v_pk_fma_f32 v[20:21], v[20:21], v[162:163], v[196:197] op_sel_hi:[1,0,1]
	v_pk_fma_f32 v[18:19], v[18:19], v[162:163], v[194:195] op_sel_hi:[1,0,1]
	v_addc_co_u32_e32 v131, vcc, 0, v131, vcc
	ds_read_b32 v140, v0 offset:8896
	s_waitcnt vmcnt(0) lgkmcnt(0)
	v_pk_fma_f32 v[4:5], v[4:5], v[140:141], v[152:153] op_sel_hi:[1,0,1]
	v_pk_fma_f32 v[2:3], v[2:3], v[140:141], v[150:151] op_sel_hi:[1,0,1]
	v_pk_fma_f32 v[152:153], v[16:17], v[140:141], v[148:149] op_sel_hi:[1,0,1]
	v_pk_fma_f32 v[150:151], v[14:15], v[140:141], v[146:147] op_sel_hi:[1,0,1]
	v_pk_fma_f32 v[136:137], v[12:13], v[140:141], v[156:157] op_sel_hi:[1,0,1]
	v_pk_fma_f32 v[134:135], v[10:11], v[140:141], v[154:155] op_sel_hi:[1,0,1]
	v_pk_fma_f32 v[16:17], v[8:9], v[140:141], v[160:161] op_sel_hi:[1,0,1]
	v_pk_fma_f32 v[14:15], v[6:7], v[140:141], v[158:159] op_sel_hi:[1,0,1]
	v_mul_f32_e32 v162, v127, v127
	flat_load_dwordx4 v[154:157], v[132:133]
	flat_load_dwordx4 v[158:161], v[130:131]
	flat_load_dwordx4 v[142:145], v[138:139] offset:16
	s_nop 0
	flat_load_dwordx4 v[130:133], v[138:139] offset:512
	flat_load_dwordx4 v[146:149], v[166:167] offset:16
	flat_load_dwordx4 v[6:9], v[138:139] offset:528
	s_nop 0
	flat_load_dwordx4 v[138:141], v[166:167] offset:512
	flat_load_dwordx4 v[10:13], v[166:167] offset:528
	v_mul_f32_e32 v163, v129, v129
	v_fmac_f32_e32 v162, v126, v126
	v_fmac_f32_e32 v163, v128, v128
	v_add_f32_e32 v162, v162, v163
	v_mul_f32_e32 v163, v123, v123
	v_mul_f32_e32 v164, v125, v125
	v_fmac_f32_e32 v163, v122, v122
	v_fmac_f32_e32 v164, v124, v124
	v_add_f32_e32 v163, v163, v164
	v_add_f32_e32 v162, v162, v163
	v_mul_f32_e32 v163, v115, v115
	v_mul_f32_e32 v164, v117, v117
	v_fmac_f32_e32 v163, v114, v114
	v_fmac_f32_e32 v164, v116, v116
	v_add_f32_e32 v163, v163, v164
	v_add_f32_e32 v162, v163, v162
	v_mul_f32_e32 v163, v107, v107
	v_mul_f32_e32 v164, v109, v109
	v_fmac_f32_e32 v163, v106, v106
	v_fmac_f32_e32 v164, v108, v108
	v_add_f32_e32 v163, v163, v164
	v_add_f32_e32 v162, v163, v162
	ds_bpermute_b32 v163, v249, v162
	s_waitcnt lgkmcnt(0)
	v_add_f32_e32 v162, v162, v163
	ds_bpermute_b32 v163, v250, v162
	s_and_saveexec_b64 s[4:5], s[10:11]
	s_cbranch_execz .LBB0_771
	s_lshl_b32 s16, s12, 10
	s_add_i32 s16, s14, s16
	v_lshl_add_u32 v164, v247, 4, s16
	s_waitcnt lgkmcnt(0)
	v_add_f32_e32 v162, v162, v163
	ds_write_b32 v164, v162
